# stack+gates-GEMM-epilogue-skips-unused-slot-loads-on-sigmoid-only-tiles
# speedup vs baseline: 1.0145x; 1.0145x over previous
;     __device__ __forceinline__ void operator()(const pg8::f32x4 (&acc)[2][2][4][2], const pg8::Unit& u, int wr, int wc, int fr, int fq) const {
;         const int row0 = u.pm * 256 + wr * 64 + fr, col0 = u.pn * 256 + wc * 32 + 8 * fq;
; #pragma unroll
;         for (int ai = 0; ai < 2; ++ai) {
;             u32x4 ld[4][2][2];
; #pragma unroll
;             for (int m = 0; m < 4; ++m)
; #pragma unroll
;                 for (int bj = 0; bj < 2; ++bj) { ld[m][bj][0] = (u32x4){0u, 0u, 0u, 0u}; ld[m][bj][1] = (u32x4){0u, 0u, 0u, 0u}; }
; #pragma unroll
;             for (int m = 0; m < 4; ++m)
; #pragma unroll
;                 for (int bj = 0; bj < 2; ++bj) f.pre(row0 + ai * 128 + m * 16, col0 + bj * 128, ld[m][bj]);
;             __builtin_amdgcn_sched_barrier(0);
; #pragma unroll
;             for (int m = 0; m < 4; ++m)
; #pragma unroll
;                 for (int bj = 0; bj < 2; ++bj) {
;                     float v[8];
; #pragma unroll
;                     for (int i = 0; i < 4; ++i) { v[i] = acc[ai][bj][m][0][i]; v[4 + i] = acc[ai][bj][m][1][i]; }
;                     f.fin(row0 + ai * 128 + m * 16, col0 + bj * 128, v, ld[m][bj]);
;     __device__ __forceinline__ void pre(int row, int col, u32x4 (&ld)[2]) const {
;         const int reg = col >> 10, c = col & 1023;
;         ld[0] = *(const u32x4*)(buf(reg) + (size_t)row * DM + c); }
.LBB0_701:
	s_lshl_b32 s45, s82, 8
	s_ashr_i32 s50, s82, 2
	s_cmp_eq_u32 s50, 1
	s_cselect_b32 s6, 0x5d00000, 0
	s_cmp_eq_u32 s50, 2
	s_cselect_b32 s7, 0x12100000, 0
	s_cmp_eq_u32 s50, 3
	s_cselect_b32 s43, 0x16100000, 0
	s_cmp_lt_i32 s50, 2
	s_cselect_b64 vcc, -1, 0
	s_add_u32 s50, s30, s6
	s_addc_u32 s51, s31, 0
	s_add_u32 s50, s50, s7
	s_addc_u32 s51, s51, 0
	v_lshl_add_u32 v100, s83, 8, v167
	s_add_u32 s52, s50, s43
	s_addc_u32 s53, s51, 0
	s_and_b32 s50, s45, 0x300
	v_ashrrev_i32_e32 v101, 31, v100
	s_cmpk_lt_u32 s45, 0x400
	v_lshlrev_b64 v[188:189], 11, v[100:101]
	v_or_b32_e32 v2, s50, v196
	s_cselect_b32 s96, 0x9d00000, 0
	v_lshl_add_u64 v[102:103], s[52:53], 0, v[188:189]
	v_lshl_add_u64 v[102:103], v[102:103], 0, s[96:97]
	v_lshlrev_b32_e32 v2, 1, v2
	v_lshl_add_u64 v[102:103], v[102:103], 0, v[2:3]
	s_cbranch_vccz .Lgates_skipld_0
	global_load_dwordx4 v[208:211], v[102:103], off
	global_load_dwordx4 v[156:159], v[102:103], off offset:256
.Lgates_skipld_0:
	v_or_b32_e32 v102, 16, v100
	v_ashrrev_i32_e32 v103, 31, v102
	v_lshlrev_b64 v[194:195], 11, v[102:103]
	v_lshl_add_u64 v[102:103], s[52:53], 0, v[194:195]
	v_lshl_add_u64 v[102:103], v[102:103], 0, s[96:97]
	v_lshl_add_u64 v[102:103], v[102:103], 0, v[2:3]
	s_cbranch_vccz .Lgates_skipld_1
	global_load_dwordx4 v[152:155], v[102:103], off
	global_load_dwordx4 v[148:151], v[102:103], off offset:256
.Lgates_skipld_1:
	v_or_b32_e32 v102, 32, v100
	v_or_b32_e32 v100, 48, v100
	v_ashrrev_i32_e32 v103, 31, v102
	v_ashrrev_i32_e32 v101, 31, v100
	v_lshlrev_b64 v[192:193], 11, v[102:103]
	v_lshlrev_b64 v[190:191], 11, v[100:101]
	v_lshl_add_u64 v[102:103], s[52:53], 0, v[192:193]
	v_lshl_add_u64 v[100:101], s[52:53], 0, v[190:191]
	v_lshl_add_u64 v[102:103], v[102:103], 0, s[96:97]
	v_lshl_add_u64 v[100:101], v[100:101], 0, s[96:97]
	v_lshl_add_u64 v[102:103], v[102:103], 0, v[2:3]
	v_lshl_add_u64 v[100:101], v[100:101], 0, v[2:3]
	s_cbranch_vccz .Lgates_skipld_2
	global_load_dwordx4 v[136:139], v[102:103], off
	global_load_dwordx4 v[124:127], v[102:103], off offset:256
	global_load_dwordx4 v[112:115], v[100:101], off
	s_nop 0
	global_load_dwordx4 v[100:103], v[100:101], off offset:256
.Lgates_skipld_2:
	s_waitcnt vmcnt(0)
	v_lshlrev_b32_e32 v170, 16, v208
	v_mul_f32_e32 v214, 0xbfb8aa3b, v144
	v_mul_f32_e32 v144, v144, v170
	v_mul_f32_e32 v170, 0xbfb8aa3b, v145
	v_exp_f32_e32 v170, v170
	v_and_b32_e32 v171, 0xffff0000, v208
	v_mul_f32_e32 v145, v145, v171
	v_lshlrev_b32_e32 v208, 16, v209
	v_add_f32_e32 v170, 1.0, v170
	v_rcp_f32_e32 v170, v170
	v_and_b32_e32 v209, 0xffff0000, v209
	v_lshlrev_b32_e32 v212, 16, v210
	v_and_b32_e32 v210, 0xffff0000, v210
	v_mul_f32_e32 v145, v170, v145
	v_cndmask_b32_e32 v145, v170, v145, vcc
	v_mul_f32_e32 v170, 0xbfb8aa3b, v146
	v_exp_f32_e32 v170, v170
	v_mul_f32_e32 v146, v146, v208
	v_lshlrev_b32_e32 v213, 16, v211
	v_exp_f32_e32 v214, v214
	v_add_f32_e32 v170, 1.0, v170
	v_rcp_f32_e32 v170, v170
	s_add_u32 s45, s30, s96
	s_addc_u32 s50, s31, 0
	v_add_f32_e32 v214, 1.0, v214
	v_mul_f32_e32 v146, v170, v146
	v_cndmask_b32_e32 v146, v170, v146, vcc
	v_mul_f32_e32 v170, 0xbfb8aa3b, v147
	v_exp_f32_e32 v170, v170
	v_mul_f32_e32 v147, v147, v209
	s_add_u32 s6, s45, s6
	v_rcp_f32_e32 v214, v214
	v_add_f32_e32 v170, 1.0, v170
	v_rcp_f32_e32 v170, v170
	s_addc_u32 s45, s50, 0
	s_add_u32 s6, s6, s7
	v_and_b32_e32 v211, 0xffff0000, v211
	v_mul_f32_e32 v147, v170, v147
	v_cndmask_b32_e32 v147, v170, v147, vcc
	v_mul_f32_e32 v170, 0xbfb8aa3b, v140
	v_exp_f32_e32 v170, v170
	v_mul_f32_e32 v140, v140, v212
	s_addc_u32 s7, s45, 0
	s_add_u32 s50, s6, s43
	v_add_f32_e32 v170, 1.0, v170
	v_rcp_f32_e32 v170, v170
	v_mul_f32_e32 v144, v214, v144
	s_addc_u32 s51, s7, 0
	v_cndmask_b32_e32 v144, v214, v144, vcc
	v_mul_f32_e32 v140, v170, v140
	v_cndmask_b32_e32 v170, v170, v140, vcc
	v_mul_f32_e32 v140, 0xbfb8aa3b, v141
	v_exp_f32_e32 v140, v140
	v_mul_f32_e32 v141, v141, v210
	v_add_f32_e32 v140, 1.0, v140
	v_rcp_f32_e32 v140, v140
	s_nop 0
	v_mul_f32_e32 v141, v140, v141
	v_cndmask_b32_e32 v171, v140, v141, vcc
	v_mul_f32_e32 v140, 0xbfb8aa3b, v142
	v_exp_f32_e32 v140, v140
	v_mul_f32_e32 v141, v142, v213
	v_cvt_pk_bf16_f32 v142, v144, v145
	v_cvt_pk_bf16_f32 v144, v170, v171
	v_add_f32_e32 v140, 1.0, v140
	v_rcp_f32_e32 v140, v140
	s_nop 0
	v_mul_f32_e32 v141, v140, v141
	v_cndmask_b32_e32 v208, v140, v141, vcc
	v_mul_f32_e32 v140, 0xbfb8aa3b, v143
	v_exp_f32_e32 v140, v140
	v_mul_f32_e32 v141, v143, v211
	v_cvt_pk_bf16_f32 v143, v146, v147
	v_lshlrev_b32_e32 v146, 16, v158
	v_add_f32_e32 v140, 1.0, v140
	v_rcp_f32_e32 v140, v140
	v_and_b32_e32 v147, 0xffff0000, v158
	v_mul_f32_e32 v158, 0xbfb8aa3b, v132
	v_exp_f32_e32 v158, v158
	v_mul_f32_e32 v141, v140, v141
	v_cndmask_b32_e32 v209, v140, v141, vcc
	v_lshl_add_u64 v[140:141], s[50:51], 0, v[188:189]
	v_lshl_add_u64 v[140:141], v[140:141], 0, v[2:3]
	v_cvt_pk_bf16_f32 v145, v208, v209
	global_store_dwordx4 v[140:141], v[142:145], off
	v_add_f32_e32 v158, 1.0, v158
	v_rcp_f32_e32 v158, v158
	v_lshlrev_b32_e32 v142, 16, v156
	v_mul_f32_e32 v132, v132, v142
	v_mul_f32_e32 v142, 0xbfb8aa3b, v133
	v_exp_f32_e32 v142, v142
	v_and_b32_e32 v143, 0xffff0000, v156
	v_mul_f32_e32 v133, v133, v143
	v_lshlrev_b32_e32 v144, 16, v157
	v_add_f32_e32 v142, 1.0, v142
	v_rcp_f32_e32 v142, v142
	v_and_b32_e32 v145, 0xffff0000, v157
	v_lshlrev_b32_e32 v156, 16, v159
	v_and_b32_e32 v157, 0xffff0000, v159
	v_mul_f32_e32 v133, v142, v133
	v_cndmask_b32_e32 v133, v142, v133, vcc
	v_mul_f32_e32 v142, 0xbfb8aa3b, v134
	v_exp_f32_e32 v142, v142
	v_mul_f32_e32 v134, v134, v144
	v_mul_f32_e32 v132, v158, v132
	v_cndmask_b32_e32 v132, v158, v132, vcc
;     __device__ __forceinline__ void operator()(const pg8::f32x4 (&acc)[2][2][4][2], const pg8::Unit& u, int wr, int wc, int fr, int fq) const {
;     ...
;             for (int m = 0; m < 4; ++m)
; #pragma unroll
;                 for (int bj = 0; bj < 2; ++bj) {
;                     float v[8];
; #pragma unroll
;                     for (int i = 0; i < 4; ++i) { v[i] = acc[ai][bj][m][0][i]; v[4 + i] = acc[ai][bj][m][1][i]; }
;                     f.fin(row0 + ai * 128 + m * 16, col0 + bj * 128, v, ld[m][bj]);
	v_add_f32_e32 v142, 1.0, v142
	v_rcp_f32_e32 v142, v142
	s_nop 0
	v_mul_f32_e32 v134, v142, v134
	v_cndmask_b32_e32 v134, v142, v134, vcc
	v_mul_f32_e32 v142, 0xbfb8aa3b, v135
	v_exp_f32_e32 v142, v142
	v_mul_f32_e32 v135, v135, v145
	v_add_f32_e32 v142, 1.0, v142
	v_rcp_f32_e32 v142, v142
	s_nop 0
	v_mul_f32_e32 v135, v142, v135
	v_cndmask_b32_e32 v135, v142, v135, vcc
	v_mul_f32_e32 v142, 0xbfb8aa3b, v128
	v_exp_f32_e32 v142, v142
	v_mul_f32_e32 v128, v128, v146
	v_add_f32_e32 v142, 1.0, v142
	v_rcp_f32_e32 v142, v142
	s_nop 0
	v_mul_f32_e32 v128, v142, v128
	v_cndmask_b32_e32 v142, v142, v128, vcc
	v_mul_f32_e32 v128, 0xbfb8aa3b, v129
	v_exp_f32_e32 v128, v128
	v_mul_f32_e32 v129, v129, v147
	v_add_f32_e32 v128, 1.0, v128
	v_rcp_f32_e32 v128, v128
	s_nop 0
	v_mul_f32_e32 v129, v128, v129
	v_cndmask_b32_e32 v143, v128, v129, vcc
	v_mul_f32_e32 v128, 0xbfb8aa3b, v130
	v_exp_f32_e32 v128, v128
	v_mul_f32_e32 v129, v130, v156
	v_cvt_pk_bf16_f32 v130, v142, v143
	v_add_f32_e32 v128, 1.0, v128
	v_rcp_f32_e32 v128, v128
	s_nop 0
	v_mul_f32_e32 v129, v128, v129
	v_cndmask_b32_e32 v144, v128, v129, vcc
	v_mul_f32_e32 v128, 0xbfb8aa3b, v131
	v_exp_f32_e32 v128, v128
	v_mul_f32_e32 v129, v131, v157
	v_add_f32_e32 v128, 1.0, v128
	v_rcp_f32_e32 v128, v128
	s_nop 0
	v_mul_f32_e32 v129, v128, v129
	v_cndmask_b32_e32 v131, v128, v129, vcc
	v_cvt_pk_bf16_f32 v128, v132, v133
	v_cvt_pk_bf16_f32 v129, v134, v135
	v_cvt_pk_bf16_f32 v131, v144, v131
	global_store_dwordx4 v[140:141], v[128:131], off offset:256
	v_mul_f32_e32 v140, 0xbfb8aa3b, v120
	v_lshlrev_b32_e32 v132, 16, v154
	v_lshlrev_b32_e32 v128, 16, v152
	v_mul_f32_e32 v120, v120, v128
	v_mul_f32_e32 v128, 0xbfb8aa3b, v121
	v_exp_f32_e32 v128, v128
	v_and_b32_e32 v129, 0xffff0000, v152
	v_mul_f32_e32 v121, v121, v129
	v_lshlrev_b32_e32 v130, 16, v153
	v_add_f32_e32 v128, 1.0, v128
	v_rcp_f32_e32 v128, v128
	v_and_b32_e32 v131, 0xffff0000, v153
	v_and_b32_e32 v133, 0xffff0000, v154
	v_lshlrev_b32_e32 v134, 16, v155
	v_mul_f32_e32 v121, v128, v121
	v_cndmask_b32_e32 v121, v128, v121, vcc
	v_mul_f32_e32 v128, 0xbfb8aa3b, v122
	v_exp_f32_e32 v128, v128
	v_mul_f32_e32 v122, v122, v130
	v_exp_f32_e32 v140, v140
	v_and_b32_e32 v135, 0xffff0000, v155
	v_add_f32_e32 v128, 1.0, v128
	v_rcp_f32_e32 v128, v128
	v_add_f32_e32 v140, 1.0, v140
	v_rcp_f32_e32 v140, v140
	v_mul_f32_e32 v122, v128, v122
	v_cndmask_b32_e32 v122, v128, v122, vcc
	v_mul_f32_e32 v128, 0xbfb8aa3b, v123
	v_exp_f32_e32 v128, v128
	v_mul_f32_e32 v123, v123, v131
	v_mul_f32_e32 v120, v140, v120
	v_cndmask_b32_e32 v120, v140, v120, vcc
	v_add_f32_e32 v128, 1.0, v128
	v_rcp_f32_e32 v128, v128
	s_nop 0
	v_mul_f32_e32 v123, v128, v123
	v_cndmask_b32_e32 v123, v128, v123, vcc
	v_mul_f32_e32 v128, 0xbfb8aa3b, v116
	v_exp_f32_e32 v128, v128
	v_mul_f32_e32 v116, v116, v132
	v_add_f32_e32 v128, 1.0, v128
	v_rcp_f32_e32 v128, v128
	s_nop 0
	v_mul_f32_e32 v116, v128, v116
	v_cndmask_b32_e32 v128, v128, v116, vcc
	v_mul_f32_e32 v116, 0xbfb8aa3b, v117
	v_exp_f32_e32 v116, v116
	v_mul_f32_e32 v117, v117, v133
	v_add_f32_e32 v116, 1.0, v116
	v_rcp_f32_e32 v116, v116
	s_nop 0
	v_mul_f32_e32 v117, v116, v117
	v_cndmask_b32_e32 v129, v116, v117, vcc
	v_mul_f32_e32 v116, 0xbfb8aa3b, v118
	v_exp_f32_e32 v116, v116
	v_mul_f32_e32 v117, v118, v134
	v_cvt_pk_bf16_f32 v118, v120, v121
	v_cvt_pk_bf16_f32 v120, v128, v129
	v_add_f32_e32 v116, 1.0, v116
	v_rcp_f32_e32 v116, v116
	v_lshlrev_b32_e32 v128, 16, v151
	v_and_b32_e32 v129, 0xffff0000, v151
	v_mul_f32_e32 v117, v116, v117
	v_cndmask_b32_e32 v130, v116, v117, vcc
	v_mul_f32_e32 v116, 0xbfb8aa3b, v119
	v_exp_f32_e32 v116, v116
	v_mul_f32_e32 v117, v119, v135
	v_cvt_pk_bf16_f32 v119, v122, v123
	v_lshlrev_b32_e32 v122, 16, v150
	v_add_f32_e32 v116, 1.0, v116
	v_rcp_f32_e32 v116, v116
	v_and_b32_e32 v123, 0xffff0000, v150
	v_mul_f32_e32 v117, v116, v117
	v_cndmask_b32_e32 v131, v116, v117, vcc
	v_lshl_add_u64 v[116:117], s[50:51], 0, v[194:195]
	v_lshl_add_u64 v[116:117], v[116:117], 0, v[2:3]
	v_cvt_pk_bf16_f32 v121, v130, v131
	global_store_dwordx4 v[116:117], v[118:121], off
	v_mul_f32_e32 v130, 0xbfb8aa3b, v108
	v_exp_f32_e32 v130, v130
	v_lshlrev_b32_e32 v118, 16, v148
	v_mul_f32_e32 v108, v108, v118
	v_mul_f32_e32 v118, 0xbfb8aa3b, v109
	v_exp_f32_e32 v118, v118
	v_and_b32_e32 v119, 0xffff0000, v148
	v_mul_f32_e32 v109, v109, v119
	v_lshlrev_b32_e32 v120, 16, v149
	v_add_f32_e32 v118, 1.0, v118
	v_rcp_f32_e32 v118, v118
	v_and_b32_e32 v121, 0xffff0000, v149
	v_add_f32_e32 v130, 1.0, v130
	v_rcp_f32_e32 v130, v130
	v_mul_f32_e32 v109, v118, v109
	v_cndmask_b32_e32 v109, v118, v109, vcc
	v_mul_f32_e32 v118, 0xbfb8aa3b, v110
	v_exp_f32_e32 v118, v118
	v_mul_f32_e32 v110, v110, v120
	v_mul_f32_e32 v108, v130, v108
	v_cndmask_b32_e32 v108, v130, v108, vcc
	v_add_f32_e32 v118, 1.0, v118
	v_rcp_f32_e32 v118, v118
	s_nop 0
	v_mul_f32_e32 v110, v118, v110
	v_cndmask_b32_e32 v110, v118, v110, vcc
	v_mul_f32_e32 v118, 0xbfb8aa3b, v111
	v_exp_f32_e32 v118, v118
	v_mul_f32_e32 v111, v111, v121
	v_add_f32_e32 v118, 1.0, v118
	v_rcp_f32_e32 v118, v118
	s_nop 0
	v_mul_f32_e32 v111, v118, v111
	v_cndmask_b32_e32 v111, v118, v111, vcc
	v_mul_f32_e32 v118, 0xbfb8aa3b, v104
	v_exp_f32_e32 v118, v118
	v_mul_f32_e32 v104, v104, v122
	v_add_f32_e32 v118, 1.0, v118
	v_rcp_f32_e32 v118, v118
	s_nop 0
	v_mul_f32_e32 v104, v118, v104
	v_cndmask_b32_e32 v118, v118, v104, vcc
	v_mul_f32_e32 v104, 0xbfb8aa3b, v105
	v_exp_f32_e32 v104, v104
	v_mul_f32_e32 v105, v105, v123
	v_add_f32_e32 v104, 1.0, v104
	v_rcp_f32_e32 v104, v104
	s_nop 0
	v_mul_f32_e32 v105, v104, v105
	v_cndmask_b32_e32 v119, v104, v105, vcc
	v_mul_f32_e32 v104, 0xbfb8aa3b, v106
;     __device__ __forceinline__ void operator()(const pg8::f32x4 (&acc)[2][2][4][2], const pg8::Unit& u, int wr, int wc, int fr, int fq) const {
;     ...
;             for (int m = 0; m < 4; ++m)
; #pragma unroll
;                 for (int bj = 0; bj < 2; ++bj) {
;                     float v[8];
; #pragma unroll
;                     for (int i = 0; i < 4; ++i) { v[i] = acc[ai][bj][m][0][i]; v[4 + i] = acc[ai][bj][m][1][i]; }
;                     f.fin(row0 + ai * 128 + m * 16, col0 + bj * 128, v, ld[m][bj]);
	v_exp_f32_e32 v104, v104
	v_mul_f32_e32 v105, v106, v128
	v_cvt_pk_bf16_f32 v106, v118, v119
	v_add_f32_e32 v104, 1.0, v104
	v_rcp_f32_e32 v104, v104
	s_nop 0
	v_mul_f32_e32 v105, v104, v105
	v_cndmask_b32_e32 v120, v104, v105, vcc
	v_mul_f32_e32 v104, 0xbfb8aa3b, v107
	v_exp_f32_e32 v104, v104
	v_mul_f32_e32 v105, v107, v129
	v_add_f32_e32 v104, 1.0, v104
	v_rcp_f32_e32 v104, v104
	s_nop 0
	v_mul_f32_e32 v105, v104, v105
	v_cndmask_b32_e32 v107, v104, v105, vcc
	v_cvt_pk_bf16_f32 v104, v108, v109
	v_cvt_pk_bf16_f32 v105, v110, v111
	v_cvt_pk_bf16_f32 v107, v120, v107
	global_store_dwordx4 v[116:117], v[104:107], off offset:256
	v_mul_f32_e32 v116, 0xbfb8aa3b, v96
	v_lshlrev_b32_e32 v108, 16, v138
	v_lshlrev_b32_e32 v104, 16, v136
	v_mul_f32_e32 v96, v96, v104
	v_mul_f32_e32 v104, 0xbfb8aa3b, v97
	v_exp_f32_e32 v104, v104
	v_and_b32_e32 v105, 0xffff0000, v136
	v_mul_f32_e32 v97, v97, v105
	v_lshlrev_b32_e32 v106, 16, v137
	v_add_f32_e32 v104, 1.0, v104
	v_rcp_f32_e32 v104, v104
	v_and_b32_e32 v107, 0xffff0000, v137
	v_and_b32_e32 v109, 0xffff0000, v138
	v_lshlrev_b32_e32 v110, 16, v139
	v_mul_f32_e32 v97, v104, v97
	v_cndmask_b32_e32 v97, v104, v97, vcc
	v_mul_f32_e32 v104, 0xbfb8aa3b, v98
	v_exp_f32_e32 v104, v104
	v_mul_f32_e32 v98, v98, v106
	v_exp_f32_e32 v116, v116
	v_and_b32_e32 v111, 0xffff0000, v139
	v_add_f32_e32 v104, 1.0, v104
	v_rcp_f32_e32 v104, v104
	v_add_f32_e32 v116, 1.0, v116
	v_rcp_f32_e32 v116, v116
	v_mul_f32_e32 v98, v104, v98
	v_cndmask_b32_e32 v98, v104, v98, vcc
	v_mul_f32_e32 v104, 0xbfb8aa3b, v99
	v_exp_f32_e32 v104, v104
	v_mul_f32_e32 v99, v99, v107
	v_mul_f32_e32 v96, v116, v96
	v_cndmask_b32_e32 v96, v116, v96, vcc
	v_add_f32_e32 v104, 1.0, v104
	v_rcp_f32_e32 v104, v104
	s_nop 0
	v_mul_f32_e32 v99, v104, v99
	v_cndmask_b32_e32 v99, v104, v99, vcc
	v_mul_f32_e32 v104, 0xbfb8aa3b, v92
	v_exp_f32_e32 v104, v104
	v_mul_f32_e32 v92, v92, v108
	v_add_f32_e32 v104, 1.0, v104
	v_rcp_f32_e32 v104, v104
	s_nop 0
	v_mul_f32_e32 v92, v104, v92
	v_cndmask_b32_e32 v104, v104, v92, vcc
	v_mul_f32_e32 v92, 0xbfb8aa3b, v93
	v_exp_f32_e32 v92, v92
	v_mul_f32_e32 v93, v93, v109
	v_add_f32_e32 v92, 1.0, v92
	v_rcp_f32_e32 v92, v92
	s_nop 0
	v_mul_f32_e32 v93, v92, v93
	v_cndmask_b32_e32 v105, v92, v93, vcc
	v_mul_f32_e32 v92, 0xbfb8aa3b, v94
	v_exp_f32_e32 v92, v92
	v_mul_f32_e32 v93, v94, v110
	v_cvt_pk_bf16_f32 v94, v96, v97
	v_cvt_pk_bf16_f32 v96, v104, v105
	v_add_f32_e32 v92, 1.0, v92
	v_rcp_f32_e32 v92, v92
	v_lshlrev_b32_e32 v104, 16, v127
	v_and_b32_e32 v105, 0xffff0000, v127
	v_mul_f32_e32 v93, v92, v93
	v_cndmask_b32_e32 v106, v92, v93, vcc
	v_mul_f32_e32 v92, 0xbfb8aa3b, v95
	v_exp_f32_e32 v92, v92
	v_mul_f32_e32 v93, v95, v111
	v_cvt_pk_bf16_f32 v95, v98, v99
	v_lshlrev_b32_e32 v98, 16, v126
	v_add_f32_e32 v92, 1.0, v92
	v_rcp_f32_e32 v92, v92
	v_and_b32_e32 v99, 0xffff0000, v126
	v_mul_f32_e32 v93, v92, v93
	v_cndmask_b32_e32 v107, v92, v93, vcc
	v_lshl_add_u64 v[92:93], s[50:51], 0, v[192:193]
	v_lshl_add_u64 v[92:93], v[92:93], 0, v[2:3]
	v_cvt_pk_bf16_f32 v97, v106, v107
	global_store_dwordx4 v[92:93], v[94:97], off
	v_mul_f32_e32 v106, 0xbfb8aa3b, v88
	v_exp_f32_e32 v106, v106
	v_lshlrev_b32_e32 v94, 16, v124
	v_mul_f32_e32 v88, v88, v94
	v_mul_f32_e32 v94, 0xbfb8aa3b, v89
	v_exp_f32_e32 v94, v94
	v_and_b32_e32 v95, 0xffff0000, v124
	v_mul_f32_e32 v89, v89, v95
	v_lshlrev_b32_e32 v96, 16, v125
	v_add_f32_e32 v94, 1.0, v94
	v_rcp_f32_e32 v94, v94
	v_and_b32_e32 v97, 0xffff0000, v125
	v_add_f32_e32 v106, 1.0, v106
	v_rcp_f32_e32 v106, v106
	v_mul_f32_e32 v89, v94, v89
	v_cndmask_b32_e32 v89, v94, v89, vcc
	v_mul_f32_e32 v94, 0xbfb8aa3b, v90
	v_exp_f32_e32 v94, v94
	v_mul_f32_e32 v90, v90, v96
	v_mul_f32_e32 v88, v106, v88
	v_cndmask_b32_e32 v88, v106, v88, vcc
	v_add_f32_e32 v94, 1.0, v94
	v_rcp_f32_e32 v94, v94
	s_nop 0
	v_mul_f32_e32 v90, v94, v90
	v_cndmask_b32_e32 v90, v94, v90, vcc
	v_mul_f32_e32 v94, 0xbfb8aa3b, v91
	v_exp_f32_e32 v94, v94
	v_mul_f32_e32 v91, v91, v97
	v_add_f32_e32 v94, 1.0, v94
	v_rcp_f32_e32 v94, v94
	s_nop 0
	v_mul_f32_e32 v91, v94, v91
	v_cndmask_b32_e32 v91, v94, v91, vcc
	v_mul_f32_e32 v94, 0xbfb8aa3b, v84
	v_exp_f32_e32 v94, v94
	v_mul_f32_e32 v84, v84, v98
	v_add_f32_e32 v94, 1.0, v94
	v_rcp_f32_e32 v94, v94
	s_nop 0
	v_mul_f32_e32 v84, v94, v84
	v_cndmask_b32_e32 v94, v94, v84, vcc
	v_mul_f32_e32 v84, 0xbfb8aa3b, v85
	v_exp_f32_e32 v84, v84
	v_mul_f32_e32 v85, v85, v99
	v_add_f32_e32 v84, 1.0, v84
	v_rcp_f32_e32 v84, v84
	s_nop 0
	v_mul_f32_e32 v85, v84, v85
	v_cndmask_b32_e32 v95, v84, v85, vcc
	v_mul_f32_e32 v84, 0xbfb8aa3b, v86
	v_exp_f32_e32 v84, v84
	v_mul_f32_e32 v85, v86, v104
	v_cvt_pk_bf16_f32 v86, v94, v95
	v_add_f32_e32 v84, 1.0, v84
	v_rcp_f32_e32 v84, v84
	s_nop 0
	v_mul_f32_e32 v85, v84, v85
	v_cndmask_b32_e32 v96, v84, v85, vcc
	v_mul_f32_e32 v84, 0xbfb8aa3b, v87
	v_exp_f32_e32 v84, v84
	v_mul_f32_e32 v85, v87, v105
	v_add_f32_e32 v84, 1.0, v84
	v_rcp_f32_e32 v84, v84
	s_nop 0
	v_mul_f32_e32 v85, v84, v85
	v_cndmask_b32_e32 v87, v84, v85, vcc
	v_cvt_pk_bf16_f32 v84, v88, v89
	v_cvt_pk_bf16_f32 v85, v90, v91
	v_cvt_pk_bf16_f32 v87, v96, v87
	global_store_dwordx4 v[92:93], v[84:87], off offset:256
	v_mul_f32_e32 v92, 0xbfb8aa3b, v80
	v_lshlrev_b32_e32 v88, 16, v114
	v_lshlrev_b32_e32 v84, 16, v112
	v_mul_f32_e32 v80, v80, v84
	v_mul_f32_e32 v84, 0xbfb8aa3b, v81
	v_exp_f32_e32 v84, v84
	v_and_b32_e32 v85, 0xffff0000, v112
	v_mul_f32_e32 v81, v81, v85
	v_lshlrev_b32_e32 v86, 16, v113
	v_add_f32_e32 v84, 1.0, v84
	v_rcp_f32_e32 v84, v84
	v_and_b32_e32 v87, 0xffff0000, v113
	v_and_b32_e32 v89, 0xffff0000, v114
	v_lshlrev_b32_e32 v90, 16, v115
	v_mul_f32_e32 v81, v84, v81
;     __device__ __forceinline__ void operator()(const pg8::f32x4 (&acc)[2][2][4][2], const pg8::Unit& u, int wr, int wc, int fr, int fq) const {
;     ...
;         for (int ai = 0; ai < 2; ++ai) {
;             u32x4 ld[4][2][2];
; #pragma unroll
;             for (int m = 0; m < 4; ++m)
; #pragma unroll
;                 for (int bj = 0; bj < 2; ++bj) { ld[m][bj][0] = (u32x4){0u, 0u, 0u, 0u}; ld[m][bj][1] = (u32x4){0u, 0u, 0u, 0u}; }
; #pragma unroll
;             for (int m = 0; m < 4; ++m)
; #pragma unroll
;                 for (int bj = 0; bj < 2; ++bj) f.pre(row0 + ai * 128 + m * 16, col0 + bj * 128, ld[m][bj]);
;             __builtin_amdgcn_sched_barrier(0);
; #pragma unroll
;             for (int m = 0; m < 4; ++m)
; #pragma unroll
;                 for (int bj = 0; bj < 2; ++bj) {
;                     float v[8];
; #pragma unroll
;                     for (int i = 0; i < 4; ++i) { v[i] = acc[ai][bj][m][0][i]; v[4 + i] = acc[ai][bj][m][1][i]; }
;                     f.fin(row0 + ai * 128 + m * 16, col0 + bj * 128, v, ld[m][bj]);
;     __device__ __forceinline__ void pre(int row, int col, u32x4 (&ld)[2]) const {
;         const int reg = col >> 10, c = col & 1023;
;         ld[0] = *(const u32x4*)(buf(reg) + (size_t)row * DM + c); }
	v_cndmask_b32_e32 v81, v84, v81, vcc
	v_mul_f32_e32 v84, 0xbfb8aa3b, v82
	v_exp_f32_e32 v84, v84
	v_mul_f32_e32 v82, v82, v86
	v_exp_f32_e32 v92, v92
	v_and_b32_e32 v91, 0xffff0000, v115
	v_add_f32_e32 v84, 1.0, v84
	v_rcp_f32_e32 v84, v84
	v_add_f32_e32 v92, 1.0, v92
	v_rcp_f32_e32 v92, v92
	v_mul_f32_e32 v82, v84, v82
	v_cndmask_b32_e32 v82, v84, v82, vcc
	v_mul_f32_e32 v84, 0xbfb8aa3b, v83
	v_exp_f32_e32 v84, v84
	v_mul_f32_e32 v83, v83, v87
	v_mul_f32_e32 v80, v92, v80
	v_cndmask_b32_e32 v80, v92, v80, vcc
	v_add_f32_e32 v84, 1.0, v84
	v_rcp_f32_e32 v84, v84
	s_nop 0
	v_mul_f32_e32 v83, v84, v83
	v_cndmask_b32_e32 v83, v84, v83, vcc
	v_mul_f32_e32 v84, 0xbfb8aa3b, v76
	v_exp_f32_e32 v84, v84
	v_mul_f32_e32 v76, v76, v88
	v_add_f32_e32 v84, 1.0, v84
	v_rcp_f32_e32 v84, v84
	s_nop 0
	v_mul_f32_e32 v76, v84, v76
	v_cndmask_b32_e32 v84, v84, v76, vcc
	v_mul_f32_e32 v76, 0xbfb8aa3b, v77
	v_exp_f32_e32 v76, v76
	v_mul_f32_e32 v77, v77, v89
	v_add_f32_e32 v76, 1.0, v76
	v_rcp_f32_e32 v76, v76
	s_nop 0
	v_mul_f32_e32 v77, v76, v77
	v_cndmask_b32_e32 v85, v76, v77, vcc
	v_mul_f32_e32 v76, 0xbfb8aa3b, v78
	v_exp_f32_e32 v76, v76
	v_mul_f32_e32 v77, v78, v90
	v_cvt_pk_bf16_f32 v78, v80, v81
	v_cvt_pk_bf16_f32 v80, v84, v85
	v_add_f32_e32 v76, 1.0, v76
	v_rcp_f32_e32 v76, v76
	v_lshlrev_b32_e32 v84, 16, v103
	v_and_b32_e32 v85, 0xffff0000, v103
	v_mul_f32_e32 v77, v76, v77
	v_cndmask_b32_e32 v86, v76, v77, vcc
	v_mul_f32_e32 v76, 0xbfb8aa3b, v79
	v_exp_f32_e32 v76, v76
	v_mul_f32_e32 v77, v79, v91
	v_cvt_pk_bf16_f32 v79, v82, v83
	v_lshlrev_b32_e32 v82, 16, v102
	v_add_f32_e32 v76, 1.0, v76
	v_rcp_f32_e32 v76, v76
	v_and_b32_e32 v83, 0xffff0000, v102
	v_mul_f32_e32 v77, v76, v77
	v_cndmask_b32_e32 v87, v76, v77, vcc
	v_lshl_add_u64 v[76:77], s[50:51], 0, v[190:191]
	v_lshl_add_u64 v[76:77], v[76:77], 0, v[2:3]
	v_cvt_pk_bf16_f32 v81, v86, v87
	global_store_dwordx4 v[76:77], v[78:81], off
	v_mul_f32_e32 v86, 0xbfb8aa3b, v72
	v_exp_f32_e32 v86, v86
	v_lshlrev_b32_e32 v78, 16, v100
	v_mul_f32_e32 v72, v72, v78
	v_mul_f32_e32 v78, 0xbfb8aa3b, v73
	v_exp_f32_e32 v78, v78
	v_and_b32_e32 v79, 0xffff0000, v100
	v_mul_f32_e32 v73, v73, v79
	v_lshlrev_b32_e32 v80, 16, v101
	v_add_f32_e32 v78, 1.0, v78
	v_rcp_f32_e32 v78, v78
	v_and_b32_e32 v81, 0xffff0000, v101
	v_add_f32_e32 v86, 1.0, v86
	v_rcp_f32_e32 v86, v86
	v_mul_f32_e32 v73, v78, v73
	v_cndmask_b32_e32 v73, v78, v73, vcc
	v_mul_f32_e32 v78, 0xbfb8aa3b, v74
	v_exp_f32_e32 v78, v78
	v_mul_f32_e32 v74, v74, v80
	v_mul_f32_e32 v72, v86, v72
	v_cndmask_b32_e32 v72, v86, v72, vcc
	v_add_f32_e32 v78, 1.0, v78
	v_rcp_f32_e32 v78, v78
	s_nop 0
	v_mul_f32_e32 v74, v78, v74
	v_cndmask_b32_e32 v74, v78, v74, vcc
	v_mul_f32_e32 v78, 0xbfb8aa3b, v75
	v_exp_f32_e32 v78, v78
	v_mul_f32_e32 v75, v75, v81
	v_add_f32_e32 v78, 1.0, v78
	v_rcp_f32_e32 v78, v78
	s_nop 0
	v_mul_f32_e32 v75, v78, v75
	v_cndmask_b32_e32 v75, v78, v75, vcc
	v_mul_f32_e32 v78, 0xbfb8aa3b, v68
	v_exp_f32_e32 v78, v78
	v_mul_f32_e32 v68, v68, v82
	v_add_f32_e32 v78, 1.0, v78
	v_rcp_f32_e32 v78, v78
	s_nop 0
	v_mul_f32_e32 v68, v78, v68
	v_cndmask_b32_e32 v78, v78, v68, vcc
	v_mul_f32_e32 v68, 0xbfb8aa3b, v69
	v_exp_f32_e32 v68, v68
	v_mul_f32_e32 v69, v69, v83
	v_add_f32_e32 v68, 1.0, v68
	v_rcp_f32_e32 v68, v68
	s_nop 0
	v_mul_f32_e32 v69, v68, v69
	v_cndmask_b32_e32 v79, v68, v69, vcc
	v_mul_f32_e32 v68, 0xbfb8aa3b, v70
	v_exp_f32_e32 v68, v68
	v_mul_f32_e32 v69, v70, v84
	v_cvt_pk_bf16_f32 v70, v78, v79
	v_add_f32_e32 v68, 1.0, v68
	v_rcp_f32_e32 v68, v68
	s_nop 0
	v_mul_f32_e32 v69, v68, v69
	v_cndmask_b32_e32 v80, v68, v69, vcc
	v_mul_f32_e32 v68, 0xbfb8aa3b, v71
	v_exp_f32_e32 v68, v68
	v_mul_f32_e32 v69, v71, v85
	v_add_f32_e32 v68, 1.0, v68
	v_rcp_f32_e32 v68, v68
	s_nop 0
	v_mul_f32_e32 v69, v68, v69
	v_cndmask_b32_e32 v71, v68, v69, vcc
	v_cvt_pk_bf16_f32 v68, v72, v73
	v_cvt_pk_bf16_f32 v69, v74, v75
	v_cvt_pk_bf16_f32 v71, v80, v71
	global_store_dwordx4 v[76:77], v[68:71], off offset:256
	v_lshl_add_u64 v[102:103], v[188:189], 0, s[10:11]
	s_nop 0
	v_lshl_add_u64 v[68:69], s[52:53], 0, v[102:103]
	v_lshl_add_u64 v[68:69], v[68:69], 0, s[96:97]
	s_mov_b64 s[6:7], 0x48000
	v_lshl_add_u64 v[68:69], v[68:69], 0, v[2:3]
	v_lshl_add_u64 v[100:101], v[188:189], 0, s[6:7]
	s_cbranch_vccz .Lgates_skipld_3
	global_load_dwordx4 v[104:107], v[68:69], off
	global_load_dwordx4 v[92:95], v[68:69], off offset:256
.Lgates_skipld_3:
	v_lshl_add_u64 v[68:69], s[52:53], 0, v[100:101]
	v_lshl_add_u64 v[68:69], v[68:69], 0, s[96:97]
	s_mov_b64 s[6:7], 0x50000
	v_lshl_add_u64 v[68:69], v[68:69], 0, v[2:3]
	v_lshl_add_u64 v[98:99], v[188:189], 0, s[6:7]
	s_cbranch_vccz .Lgates_skipld_4
	global_load_dwordx4 v[88:91], v[68:69], off
	global_load_dwordx4 v[84:87], v[68:69], off offset:256
.Lgates_skipld_4:
	v_lshl_add_u64 v[68:69], s[52:53], 0, v[98:99]
	v_lshl_add_u64 v[68:69], v[68:69], 0, s[96:97]
	s_mov_b64 s[6:7], 0x58000
	v_lshl_add_u64 v[68:69], v[68:69], 0, v[2:3]
	v_lshl_add_u64 v[96:97], v[188:189], 0, s[6:7]
	s_cbranch_vccz .Lgates_skipld_5
	global_load_dwordx4 v[80:83], v[68:69], off
	global_load_dwordx4 v[76:79], v[68:69], off offset:256
.Lgates_skipld_5:
	v_lshl_add_u64 v[68:69], s[52:53], 0, v[96:97]
	v_lshl_add_u64 v[68:69], v[68:69], 0, s[96:97]
	v_lshl_add_u64 v[68:69], v[68:69], 0, v[2:3]
	s_cbranch_vccz .Lgates_skipld_6
	global_load_dwordx4 v[72:75], v[68:69], off
	s_nop 0
	global_load_dwordx4 v[68:71], v[68:69], off offset:256
;     __device__ __forceinline__ void operator()(const pg8::f32x4 (&acc)[2][2][4][2], const pg8::Unit& u, int wr, int wc, int fr, int fq) const {
;     ...
;             for (int m = 0; m < 4; ++m)
; #pragma unroll
;                 for (int bj = 0; bj < 2; ++bj) {
;                     float v[8];
; #pragma unroll
;                     for (int i = 0; i < 4; ++i) { v[i] = acc[ai][bj][m][0][i]; v[4 + i] = acc[ai][bj][m][1][i]; }
;                     f.fin(row0 + ai * 128 + m * 16, col0 + bj * 128, v, ld[m][bj]);
.Lgates_skipld_6:
	s_waitcnt vmcnt(7)
	v_lshlrev_b32_e32 v108, 16, v104
	v_and_b32_e32 v104, 0xffff0000, v104
	v_mul_f32_e32 v112, 0xbfb8aa3b, v64
	v_mul_f32_e32 v64, v64, v108
	v_mul_f32_e32 v108, 0xbfb8aa3b, v65
	v_mul_f32_e32 v65, v65, v104
	v_mul_f32_e32 v104, 0xbfb8aa3b, v66
	v_exp_f32_e32 v104, v104
	v_lshlrev_b32_e32 v109, 16, v105
	v_mul_f32_e32 v66, v66, v109
	v_and_b32_e32 v105, 0xffff0000, v105
	v_add_f32_e32 v104, 1.0, v104
	v_rcp_f32_e32 v104, v104
	v_lshlrev_b32_e32 v110, 16, v106
	v_and_b32_e32 v106, 0xffff0000, v106
	v_lshlrev_b32_e32 v111, 16, v107
	v_mul_f32_e32 v66, v104, v66
	v_cndmask_b32_e32 v66, v104, v66, vcc
	v_mul_f32_e32 v104, 0xbfb8aa3b, v67
	v_exp_f32_e32 v104, v104
	v_mul_f32_e32 v67, v67, v105
	v_exp_f32_e32 v112, v112
	v_exp_f32_e32 v108, v108
	v_add_f32_e32 v104, 1.0, v104
	v_rcp_f32_e32 v104, v104
	v_add_f32_e32 v112, 1.0, v112
	v_add_f32_e32 v108, 1.0, v108
	v_rcp_f32_e32 v112, v112
	v_mul_f32_e32 v67, v104, v67
	v_cndmask_b32_e32 v67, v104, v67, vcc
	v_mul_f32_e32 v104, 0xbfb8aa3b, v60
	v_exp_f32_e32 v104, v104
	v_mul_f32_e32 v60, v60, v110
	v_rcp_f32_e32 v108, v108
	v_and_b32_e32 v107, 0xffff0000, v107
	v_add_f32_e32 v104, 1.0, v104
	v_rcp_f32_e32 v104, v104
	v_mul_f32_e32 v64, v112, v64
	v_mul_f32_e32 v65, v108, v65
	v_cndmask_b32_e32 v64, v112, v64, vcc
	v_mul_f32_e32 v60, v104, v60
	v_cndmask_b32_e32 v104, v104, v60, vcc
	v_mul_f32_e32 v60, 0xbfb8aa3b, v61
	v_exp_f32_e32 v60, v60
	v_mul_f32_e32 v61, v61, v106
	v_cndmask_b32_e32 v65, v108, v65, vcc
	v_add_f32_e32 v60, 1.0, v60
	v_rcp_f32_e32 v60, v60
	s_nop 0
	v_mul_f32_e32 v61, v60, v61
	v_cndmask_b32_e32 v105, v60, v61, vcc
	v_mul_f32_e32 v60, 0xbfb8aa3b, v62
	v_exp_f32_e32 v60, v60
	v_mul_f32_e32 v61, v62, v111
	v_cvt_pk_bf16_f32 v62, v64, v65
	v_cvt_pk_bf16_f32 v64, v104, v105
	v_add_f32_e32 v60, 1.0, v60
	v_rcp_f32_e32 v60, v60
	s_nop 0
	v_mul_f32_e32 v61, v60, v61
	v_cndmask_b32_e32 v106, v60, v61, vcc
	v_mul_f32_e32 v60, 0xbfb8aa3b, v63
	v_exp_f32_e32 v60, v60
	v_mul_f32_e32 v61, v63, v107
	v_cvt_pk_bf16_f32 v63, v66, v67
	s_waitcnt vmcnt(6)
	v_lshlrev_b32_e32 v66, 16, v94
	v_add_f32_e32 v60, 1.0, v60
	v_rcp_f32_e32 v60, v60
	v_and_b32_e32 v67, 0xffff0000, v94
	v_mul_f32_e32 v94, 0xbfb8aa3b, v56
	v_exp_f32_e32 v94, v94
	v_mul_f32_e32 v61, v60, v61
	v_cndmask_b32_e32 v107, v60, v61, vcc
	v_lshl_add_u64 v[60:61], s[50:51], 0, v[102:103]
	v_lshl_add_u64 v[60:61], v[60:61], 0, v[2:3]
	v_cvt_pk_bf16_f32 v65, v106, v107
	global_store_dwordx4 v[60:61], v[62:65], off
	v_add_f32_e32 v94, 1.0, v94
	v_rcp_f32_e32 v94, v94
	v_lshlrev_b32_e32 v62, 16, v92
	v_mul_f32_e32 v56, v56, v62
	v_mul_f32_e32 v62, 0xbfb8aa3b, v57
	v_exp_f32_e32 v62, v62
	v_and_b32_e32 v63, 0xffff0000, v92
	v_mul_f32_e32 v57, v57, v63
	v_lshlrev_b32_e32 v64, 16, v93
	v_add_f32_e32 v62, 1.0, v62
	v_rcp_f32_e32 v62, v62
	v_and_b32_e32 v65, 0xffff0000, v93
	v_lshlrev_b32_e32 v92, 16, v95
	v_and_b32_e32 v93, 0xffff0000, v95
	v_mul_f32_e32 v57, v62, v57
	v_cndmask_b32_e32 v57, v62, v57, vcc
	v_mul_f32_e32 v62, 0xbfb8aa3b, v58
	v_exp_f32_e32 v62, v62
	v_mul_f32_e32 v58, v58, v64
	v_mul_f32_e32 v56, v94, v56
	v_cndmask_b32_e32 v56, v94, v56, vcc
	v_add_f32_e32 v62, 1.0, v62
	v_rcp_f32_e32 v62, v62
	s_nop 0
	v_mul_f32_e32 v58, v62, v58
	v_cndmask_b32_e32 v58, v62, v58, vcc
	v_mul_f32_e32 v62, 0xbfb8aa3b, v59
	v_exp_f32_e32 v62, v62
	v_mul_f32_e32 v59, v59, v65
	v_add_f32_e32 v62, 1.0, v62
	v_rcp_f32_e32 v62, v62
	s_nop 0
	v_mul_f32_e32 v59, v62, v59
	v_cndmask_b32_e32 v59, v62, v59, vcc
	v_mul_f32_e32 v62, 0xbfb8aa3b, v52
	v_exp_f32_e32 v62, v62
	v_mul_f32_e32 v52, v52, v66
	v_add_f32_e32 v62, 1.0, v62
	v_rcp_f32_e32 v62, v62
	s_nop 0
	v_mul_f32_e32 v52, v62, v52
	v_cndmask_b32_e32 v62, v62, v52, vcc
	v_mul_f32_e32 v52, 0xbfb8aa3b, v53
	v_exp_f32_e32 v52, v52
	v_mul_f32_e32 v53, v53, v67
	v_add_f32_e32 v52, 1.0, v52
	v_rcp_f32_e32 v52, v52
	s_nop 0
	v_mul_f32_e32 v53, v52, v53
	v_cndmask_b32_e32 v63, v52, v53, vcc
	v_mul_f32_e32 v52, 0xbfb8aa3b, v54
	v_exp_f32_e32 v52, v52
	v_mul_f32_e32 v53, v54, v92
	v_cvt_pk_bf16_f32 v54, v62, v63
	v_add_f32_e32 v52, 1.0, v52
	v_rcp_f32_e32 v52, v52
	s_nop 0
	v_mul_f32_e32 v53, v52, v53
	v_cndmask_b32_e32 v64, v52, v53, vcc
	v_mul_f32_e32 v52, 0xbfb8aa3b, v55
	v_exp_f32_e32 v52, v52
	v_mul_f32_e32 v53, v55, v93
	v_add_f32_e32 v52, 1.0, v52
	v_rcp_f32_e32 v52, v52
	s_nop 0
	v_mul_f32_e32 v53, v52, v53
	v_cndmask_b32_e32 v55, v52, v53, vcc
	v_cvt_pk_bf16_f32 v52, v56, v57
	v_cvt_pk_bf16_f32 v53, v58, v59
	v_cvt_pk_bf16_f32 v55, v64, v55
	global_store_dwordx4 v[60:61], v[52:55], off offset:256
	v_mul_f32_e32 v60, 0xbfb8aa3b, v48
	s_waitcnt vmcnt(7)
	v_lshlrev_b32_e32 v56, 16, v90
	v_lshlrev_b32_e32 v52, 16, v88
	v_mul_f32_e32 v48, v48, v52
	v_mul_f32_e32 v52, 0xbfb8aa3b, v49
	v_exp_f32_e32 v52, v52
	v_and_b32_e32 v53, 0xffff0000, v88
	v_mul_f32_e32 v49, v49, v53
	v_lshlrev_b32_e32 v54, 16, v89
	v_add_f32_e32 v52, 1.0, v52
	v_rcp_f32_e32 v52, v52
	v_and_b32_e32 v55, 0xffff0000, v89
	v_and_b32_e32 v57, 0xffff0000, v90
	v_lshlrev_b32_e32 v58, 16, v91
	v_mul_f32_e32 v49, v52, v49
	v_cndmask_b32_e32 v49, v52, v49, vcc
	v_mul_f32_e32 v52, 0xbfb8aa3b, v50
	v_exp_f32_e32 v52, v52
	v_mul_f32_e32 v50, v50, v54
	v_exp_f32_e32 v60, v60
	v_and_b32_e32 v59, 0xffff0000, v91
	v_add_f32_e32 v52, 1.0, v52
	v_rcp_f32_e32 v52, v52
	v_add_f32_e32 v60, 1.0, v60
	v_rcp_f32_e32 v60, v60
	v_mul_f32_e32 v50, v52, v50
	v_cndmask_b32_e32 v50, v52, v50, vcc
	v_mul_f32_e32 v52, 0xbfb8aa3b, v51
	v_exp_f32_e32 v52, v52
	v_mul_f32_e32 v51, v51, v55
	v_mul_f32_e32 v48, v60, v48
	v_cndmask_b32_e32 v48, v60, v48, vcc
	v_add_f32_e32 v52, 1.0, v52
	v_rcp_f32_e32 v52, v52
	s_nop 0
	v_mul_f32_e32 v51, v52, v51
	v_cndmask_b32_e32 v51, v52, v51, vcc
	v_mul_f32_e32 v52, 0xbfb8aa3b, v44
	v_exp_f32_e32 v52, v52
	v_mul_f32_e32 v44, v44, v56
	v_add_f32_e32 v52, 1.0, v52
	v_rcp_f32_e32 v52, v52
	s_nop 0
	v_mul_f32_e32 v44, v52, v44
	v_cndmask_b32_e32 v52, v52, v44, vcc
	v_mul_f32_e32 v44, 0xbfb8aa3b, v45
	v_exp_f32_e32 v44, v44
	v_mul_f32_e32 v45, v45, v57
	v_add_f32_e32 v44, 1.0, v44
	v_rcp_f32_e32 v44, v44
	s_nop 0
	v_mul_f32_e32 v45, v44, v45
	v_cndmask_b32_e32 v53, v44, v45, vcc
	v_mul_f32_e32 v44, 0xbfb8aa3b, v46
	v_exp_f32_e32 v44, v44
	v_mul_f32_e32 v45, v46, v58
	v_cvt_pk_bf16_f32 v46, v48, v49
	v_cvt_pk_bf16_f32 v48, v52, v53
	v_add_f32_e32 v44, 1.0, v44
	v_rcp_f32_e32 v44, v44
	s_waitcnt vmcnt(6)
;     __device__ __forceinline__ void operator()(const pg8::f32x4 (&acc)[2][2][4][2], const pg8::Unit& u, int wr, int wc, int fr, int fq) const {
;     ...
;             for (int m = 0; m < 4; ++m)
; #pragma unroll
;                 for (int bj = 0; bj < 2; ++bj) {
;                     float v[8];
; #pragma unroll
;                     for (int i = 0; i < 4; ++i) { v[i] = acc[ai][bj][m][0][i]; v[4 + i] = acc[ai][bj][m][1][i]; }
;                     f.fin(row0 + ai * 128 + m * 16, col0 + bj * 128, v, ld[m][bj]);
	v_lshlrev_b32_e32 v52, 16, v87
	v_and_b32_e32 v53, 0xffff0000, v87
	v_mul_f32_e32 v45, v44, v45
	v_cndmask_b32_e32 v54, v44, v45, vcc
	v_mul_f32_e32 v44, 0xbfb8aa3b, v47
	v_exp_f32_e32 v44, v44
	v_mul_f32_e32 v45, v47, v59
	v_cvt_pk_bf16_f32 v47, v50, v51
	v_lshlrev_b32_e32 v50, 16, v86
	v_add_f32_e32 v44, 1.0, v44
	v_rcp_f32_e32 v44, v44
	v_and_b32_e32 v51, 0xffff0000, v86
	v_mul_f32_e32 v45, v44, v45
	v_cndmask_b32_e32 v55, v44, v45, vcc
	v_lshl_add_u64 v[44:45], s[50:51], 0, v[100:101]
	v_lshl_add_u64 v[44:45], v[44:45], 0, v[2:3]
	v_cvt_pk_bf16_f32 v49, v54, v55
	global_store_dwordx4 v[44:45], v[46:49], off
	v_mul_f32_e32 v54, 0xbfb8aa3b, v40
	v_exp_f32_e32 v54, v54
	v_lshlrev_b32_e32 v46, 16, v84
	v_mul_f32_e32 v40, v40, v46
	v_mul_f32_e32 v46, 0xbfb8aa3b, v41
	v_exp_f32_e32 v46, v46
	v_and_b32_e32 v47, 0xffff0000, v84
	v_mul_f32_e32 v41, v41, v47
	v_lshlrev_b32_e32 v48, 16, v85
	v_add_f32_e32 v46, 1.0, v46
	v_rcp_f32_e32 v46, v46
	v_and_b32_e32 v49, 0xffff0000, v85
	v_add_f32_e32 v54, 1.0, v54
	v_rcp_f32_e32 v54, v54
	v_mul_f32_e32 v41, v46, v41
	v_cndmask_b32_e32 v41, v46, v41, vcc
	v_mul_f32_e32 v46, 0xbfb8aa3b, v42
	v_exp_f32_e32 v46, v46
	v_mul_f32_e32 v42, v42, v48
	v_mul_f32_e32 v40, v54, v40
	v_cndmask_b32_e32 v40, v54, v40, vcc
	v_add_f32_e32 v46, 1.0, v46
	v_rcp_f32_e32 v46, v46
	s_nop 0
	v_mul_f32_e32 v42, v46, v42
	v_cndmask_b32_e32 v42, v46, v42, vcc
	v_mul_f32_e32 v46, 0xbfb8aa3b, v43
	v_exp_f32_e32 v46, v46
	v_mul_f32_e32 v43, v43, v49
	v_add_f32_e32 v46, 1.0, v46
	v_rcp_f32_e32 v46, v46
	s_nop 0
	v_mul_f32_e32 v43, v46, v43
	v_cndmask_b32_e32 v43, v46, v43, vcc
	v_mul_f32_e32 v46, 0xbfb8aa3b, v36
	v_exp_f32_e32 v46, v46
	v_mul_f32_e32 v36, v36, v50
	v_add_f32_e32 v46, 1.0, v46
	v_rcp_f32_e32 v46, v46
	s_nop 0
	v_mul_f32_e32 v36, v46, v36
	v_cndmask_b32_e32 v46, v46, v36, vcc
	v_mul_f32_e32 v36, 0xbfb8aa3b, v37
	v_exp_f32_e32 v36, v36
	v_mul_f32_e32 v37, v37, v51
	v_add_f32_e32 v36, 1.0, v36
	v_rcp_f32_e32 v36, v36
	s_nop 0
	v_mul_f32_e32 v37, v36, v37
	v_cndmask_b32_e32 v47, v36, v37, vcc
	v_mul_f32_e32 v36, 0xbfb8aa3b, v38
	v_exp_f32_e32 v36, v36
	v_mul_f32_e32 v37, v38, v52
	v_cvt_pk_bf16_f32 v38, v46, v47
	v_add_f32_e32 v36, 1.0, v36
	v_rcp_f32_e32 v36, v36
	s_nop 0
	v_mul_f32_e32 v37, v36, v37
	v_cndmask_b32_e32 v48, v36, v37, vcc
	v_mul_f32_e32 v36, 0xbfb8aa3b, v39
	v_exp_f32_e32 v36, v36
	v_mul_f32_e32 v37, v39, v53
	v_add_f32_e32 v36, 1.0, v36
	v_rcp_f32_e32 v36, v36
	s_nop 0
	v_mul_f32_e32 v37, v36, v37
	v_cndmask_b32_e32 v39, v36, v37, vcc
	v_cvt_pk_bf16_f32 v36, v40, v41
	v_cvt_pk_bf16_f32 v37, v42, v43
	v_cvt_pk_bf16_f32 v39, v48, v39
	global_store_dwordx4 v[44:45], v[36:39], off offset:256
	v_mul_f32_e32 v44, 0xbfb8aa3b, v32
	s_waitcnt vmcnt(7)
	v_lshlrev_b32_e32 v40, 16, v82
	v_lshlrev_b32_e32 v36, 16, v80
	v_mul_f32_e32 v32, v32, v36
	v_mul_f32_e32 v36, 0xbfb8aa3b, v33
	v_exp_f32_e32 v36, v36
	v_and_b32_e32 v37, 0xffff0000, v80
	v_mul_f32_e32 v33, v33, v37
	v_lshlrev_b32_e32 v38, 16, v81
	v_add_f32_e32 v36, 1.0, v36
	v_rcp_f32_e32 v36, v36
	v_and_b32_e32 v39, 0xffff0000, v81
	v_and_b32_e32 v41, 0xffff0000, v82
	v_lshlrev_b32_e32 v42, 16, v83
	v_mul_f32_e32 v33, v36, v33
	v_cndmask_b32_e32 v33, v36, v33, vcc
	v_mul_f32_e32 v36, 0xbfb8aa3b, v34
	v_exp_f32_e32 v36, v36
	v_mul_f32_e32 v34, v34, v38
	v_exp_f32_e32 v44, v44
	v_and_b32_e32 v43, 0xffff0000, v83
	v_add_f32_e32 v36, 1.0, v36
	v_rcp_f32_e32 v36, v36
	v_add_f32_e32 v44, 1.0, v44
	v_rcp_f32_e32 v44, v44
	v_mul_f32_e32 v34, v36, v34
	v_cndmask_b32_e32 v34, v36, v34, vcc
	v_mul_f32_e32 v36, 0xbfb8aa3b, v35
	v_exp_f32_e32 v36, v36
	v_mul_f32_e32 v35, v35, v39
	v_mul_f32_e32 v32, v44, v32
	v_cndmask_b32_e32 v32, v44, v32, vcc
	v_add_f32_e32 v36, 1.0, v36
	v_rcp_f32_e32 v36, v36
	s_nop 0
	v_mul_f32_e32 v35, v36, v35
	v_cndmask_b32_e32 v35, v36, v35, vcc
	v_mul_f32_e32 v36, 0xbfb8aa3b, v28
	v_exp_f32_e32 v36, v36
	v_mul_f32_e32 v28, v28, v40
	v_add_f32_e32 v36, 1.0, v36
	v_rcp_f32_e32 v36, v36
	s_nop 0
	v_mul_f32_e32 v28, v36, v28
	v_cndmask_b32_e32 v36, v36, v28, vcc
	v_mul_f32_e32 v28, 0xbfb8aa3b, v29
	v_exp_f32_e32 v28, v28
	v_mul_f32_e32 v29, v29, v41
	v_add_f32_e32 v28, 1.0, v28
	v_rcp_f32_e32 v28, v28
	s_nop 0
	v_mul_f32_e32 v29, v28, v29
	v_cndmask_b32_e32 v37, v28, v29, vcc
	v_mul_f32_e32 v28, 0xbfb8aa3b, v30
	v_exp_f32_e32 v28, v28
	v_mul_f32_e32 v29, v30, v42
	v_cvt_pk_bf16_f32 v30, v32, v33
	v_cvt_pk_bf16_f32 v32, v36, v37
	v_add_f32_e32 v28, 1.0, v28
	v_rcp_f32_e32 v28, v28
	s_waitcnt vmcnt(6)
;     __device__ __forceinline__ void operator()(const pg8::f32x4 (&acc)[2][2][4][2], const pg8::Unit& u, int wr, int wc, int fr, int fq) const {
;     ...
;             for (int m = 0; m < 4; ++m)
; #pragma unroll
;                 for (int bj = 0; bj < 2; ++bj) {
;                     float v[8];
; #pragma unroll
;                     for (int i = 0; i < 4; ++i) { v[i] = acc[ai][bj][m][0][i]; v[4 + i] = acc[ai][bj][m][1][i]; }
;                     f.fin(row0 + ai * 128 + m * 16, col0 + bj * 128, v, ld[m][bj]);
	v_lshlrev_b32_e32 v36, 16, v79
	v_and_b32_e32 v37, 0xffff0000, v79
	v_mul_f32_e32 v29, v28, v29
	v_cndmask_b32_e32 v38, v28, v29, vcc
	v_mul_f32_e32 v28, 0xbfb8aa3b, v31
	v_exp_f32_e32 v28, v28
	v_mul_f32_e32 v29, v31, v43
	v_cvt_pk_bf16_f32 v31, v34, v35
	v_lshlrev_b32_e32 v34, 16, v78
	v_add_f32_e32 v28, 1.0, v28
	v_rcp_f32_e32 v28, v28
	v_and_b32_e32 v35, 0xffff0000, v78
	v_mul_f32_e32 v29, v28, v29
	v_cndmask_b32_e32 v39, v28, v29, vcc
	v_lshl_add_u64 v[28:29], s[50:51], 0, v[98:99]
	v_lshl_add_u64 v[28:29], v[28:29], 0, v[2:3]
	v_cvt_pk_bf16_f32 v33, v38, v39
	global_store_dwordx4 v[28:29], v[30:33], off
	v_mul_f32_e32 v38, 0xbfb8aa3b, v24
	v_exp_f32_e32 v38, v38
	v_lshlrev_b32_e32 v30, 16, v76
	v_mul_f32_e32 v24, v24, v30
	v_mul_f32_e32 v30, 0xbfb8aa3b, v25
	v_exp_f32_e32 v30, v30
	v_and_b32_e32 v31, 0xffff0000, v76
	v_mul_f32_e32 v25, v25, v31
	v_lshlrev_b32_e32 v32, 16, v77
	v_add_f32_e32 v30, 1.0, v30
	v_rcp_f32_e32 v30, v30
	v_and_b32_e32 v33, 0xffff0000, v77
	v_add_f32_e32 v38, 1.0, v38
	v_rcp_f32_e32 v38, v38
	v_mul_f32_e32 v25, v30, v25
	v_cndmask_b32_e32 v25, v30, v25, vcc
	v_mul_f32_e32 v30, 0xbfb8aa3b, v26
	v_exp_f32_e32 v30, v30
	v_mul_f32_e32 v26, v26, v32
	v_mul_f32_e32 v24, v38, v24
	v_cndmask_b32_e32 v24, v38, v24, vcc
	v_add_f32_e32 v30, 1.0, v30
	v_rcp_f32_e32 v30, v30
	s_nop 0
	v_mul_f32_e32 v26, v30, v26
	v_cndmask_b32_e32 v26, v30, v26, vcc
	v_mul_f32_e32 v30, 0xbfb8aa3b, v27
	v_exp_f32_e32 v30, v30
	v_mul_f32_e32 v27, v27, v33
	v_add_f32_e32 v30, 1.0, v30
	v_rcp_f32_e32 v30, v30
	s_nop 0
	v_mul_f32_e32 v27, v30, v27
	v_cndmask_b32_e32 v27, v30, v27, vcc
	v_mul_f32_e32 v30, 0xbfb8aa3b, v20
	v_exp_f32_e32 v30, v30
	v_mul_f32_e32 v20, v20, v34
	v_add_f32_e32 v30, 1.0, v30
	v_rcp_f32_e32 v30, v30
	s_nop 0
	v_mul_f32_e32 v20, v30, v20
	v_cndmask_b32_e32 v30, v30, v20, vcc
	v_mul_f32_e32 v20, 0xbfb8aa3b, v21
	v_exp_f32_e32 v20, v20
	v_mul_f32_e32 v21, v21, v35
	v_add_f32_e32 v20, 1.0, v20
	v_rcp_f32_e32 v20, v20
	s_nop 0
	v_mul_f32_e32 v21, v20, v21
	v_cndmask_b32_e32 v31, v20, v21, vcc
	v_mul_f32_e32 v20, 0xbfb8aa3b, v22
	v_exp_f32_e32 v20, v20
	v_mul_f32_e32 v21, v22, v36
	v_cvt_pk_bf16_f32 v22, v30, v31
	v_add_f32_e32 v20, 1.0, v20
	v_rcp_f32_e32 v20, v20
	s_nop 0
	v_mul_f32_e32 v21, v20, v21
	v_cndmask_b32_e32 v32, v20, v21, vcc
	v_mul_f32_e32 v20, 0xbfb8aa3b, v23
	v_exp_f32_e32 v20, v20
	v_mul_f32_e32 v21, v23, v37
	v_add_f32_e32 v20, 1.0, v20
	v_rcp_f32_e32 v20, v20
	s_nop 0
	v_mul_f32_e32 v21, v20, v21
	v_cndmask_b32_e32 v23, v20, v21, vcc
	v_cvt_pk_bf16_f32 v20, v24, v25
	v_cvt_pk_bf16_f32 v21, v26, v27
	v_cvt_pk_bf16_f32 v23, v32, v23
	global_store_dwordx4 v[28:29], v[20:23], off offset:256
	v_mul_f32_e32 v28, 0xbfb8aa3b, v16
	s_waitcnt vmcnt(7)
; #define PG8_BAR __builtin_amdgcn_s_barrier()
; template <class Epi, class Sched, bool ALIGN_EPI = false, bool SP2 = false>
; __device__ __forceinline__ void gemm_phase(PG8_LAS unsigned char* lds, const Gemm g, const Sched& S, const Epi& E) {
;     ...
;         if (!has_next) break;
; #pragma unroll
;         for (int a = 0; a < 2; ++a)
; #pragma unroll
;             for (int b = 0; b < 2; ++b)
; #pragma unroll
;                 for (int m = 0; m < 4; ++m)
; #pragma unroll
;                     for (int n = 0; n < 2; ++n) acc[a][b][m][n] = (f32x4){0.f, 0.f, 0.f, 0.f};
;         cur = nxt; cA = nA; cB = nB; ++ui;
;         if constexpr (ALIGN_EPI) { if (wr == 1) PG8_BAR; }
	v_lshlrev_b32_e32 v24, 16, v74
	v_lshlrev_b32_e32 v20, 16, v72
	v_mul_f32_e32 v16, v16, v20
	v_mul_f32_e32 v20, 0xbfb8aa3b, v17
	v_exp_f32_e32 v20, v20
	v_and_b32_e32 v21, 0xffff0000, v72
	v_mul_f32_e32 v17, v17, v21
	v_lshlrev_b32_e32 v22, 16, v73
	v_add_f32_e32 v20, 1.0, v20
	v_rcp_f32_e32 v20, v20
	v_and_b32_e32 v23, 0xffff0000, v73
	v_and_b32_e32 v25, 0xffff0000, v74
	v_lshlrev_b32_e32 v26, 16, v75
	v_mul_f32_e32 v17, v20, v17
	v_cndmask_b32_e32 v17, v20, v17, vcc
	v_mul_f32_e32 v20, 0xbfb8aa3b, v18
	v_exp_f32_e32 v20, v20
	v_mul_f32_e32 v18, v18, v22
	v_exp_f32_e32 v28, v28
	v_and_b32_e32 v27, 0xffff0000, v75
	v_add_f32_e32 v20, 1.0, v20
	v_rcp_f32_e32 v20, v20
	v_add_f32_e32 v28, 1.0, v28
	v_rcp_f32_e32 v28, v28
	v_mul_f32_e32 v18, v20, v18
	v_cndmask_b32_e32 v18, v20, v18, vcc
	v_mul_f32_e32 v20, 0xbfb8aa3b, v19
	v_exp_f32_e32 v20, v20
	v_mul_f32_e32 v19, v19, v23
	v_mul_f32_e32 v16, v28, v16
	v_cndmask_b32_e32 v16, v28, v16, vcc
	v_add_f32_e32 v20, 1.0, v20
	v_rcp_f32_e32 v20, v20
	s_nop 0
	v_mul_f32_e32 v19, v20, v19
	v_cndmask_b32_e32 v19, v20, v19, vcc
	v_mul_f32_e32 v20, 0xbfb8aa3b, v12
	v_exp_f32_e32 v20, v20
	v_mul_f32_e32 v12, v12, v24
	v_add_f32_e32 v20, 1.0, v20
	v_rcp_f32_e32 v20, v20
	s_nop 0
	v_mul_f32_e32 v12, v20, v12
	v_cndmask_b32_e32 v20, v20, v12, vcc
	v_mul_f32_e32 v12, 0xbfb8aa3b, v13
	v_exp_f32_e32 v12, v12
	v_mul_f32_e32 v13, v13, v25
	v_add_f32_e32 v12, 1.0, v12
	v_rcp_f32_e32 v12, v12
	s_nop 0
	v_mul_f32_e32 v13, v12, v13
	v_cndmask_b32_e32 v21, v12, v13, vcc
	v_mul_f32_e32 v12, 0xbfb8aa3b, v14
	v_exp_f32_e32 v12, v12
	v_mul_f32_e32 v13, v14, v26
	v_cvt_pk_bf16_f32 v14, v16, v17
	v_cvt_pk_bf16_f32 v16, v20, v21
	v_add_f32_e32 v12, 1.0, v12
	v_rcp_f32_e32 v12, v12
	v_mul_f32_e32 v21, 0xbfb8aa3b, v8
	v_exp_f32_e32 v21, v21
	s_waitcnt vmcnt(6)
	v_and_b32_e32 v20, 0xffff0000, v71
	v_mul_f32_e32 v13, v12, v13
	v_cndmask_b32_e32 v22, v12, v13, vcc
	v_mul_f32_e32 v12, 0xbfb8aa3b, v15
	v_exp_f32_e32 v12, v12
	v_mul_f32_e32 v13, v15, v27
	v_cvt_pk_bf16_f32 v15, v18, v19
	v_and_b32_e32 v18, 0xffff0000, v70
	v_add_f32_e32 v12, 1.0, v12
	v_rcp_f32_e32 v12, v12
	v_lshlrev_b32_e32 v19, 16, v71
	v_add_f32_e32 v21, 1.0, v21
	v_rcp_f32_e32 v21, v21
	v_mul_f32_e32 v13, v12, v13
	v_cndmask_b32_e32 v23, v12, v13, vcc
	v_lshl_add_u64 v[12:13], s[50:51], 0, v[96:97]
	v_lshl_add_u64 v[12:13], v[12:13], 0, v[2:3]
	v_lshlrev_b32_e32 v2, 16, v68
	v_mul_f32_e32 v2, v8, v2
	v_mul_f32_e32 v8, 0xbfb8aa3b, v9
	v_exp_f32_e32 v8, v8
	v_cvt_pk_bf16_f32 v17, v22, v23
	global_store_dwordx4 v[12:13], v[14:17], off
	v_mul_f32_e32 v2, v21, v2
	v_add_f32_e32 v8, 1.0, v8
	v_rcp_f32_e32 v8, v8
	v_and_b32_e32 v14, 0xffff0000, v68
	v_mul_f32_e32 v9, v9, v14
	v_lshlrev_b32_e32 v15, 16, v69
	v_mul_f32_e32 v9, v8, v9
	v_cndmask_b32_e32 v8, v8, v9, vcc
	v_mul_f32_e32 v9, 0xbfb8aa3b, v10
	v_exp_f32_e32 v9, v9
	v_mul_f32_e32 v10, v10, v15
	v_and_b32_e32 v16, 0xffff0000, v69
	v_lshlrev_b32_e32 v17, 16, v70
	v_add_f32_e32 v9, 1.0, v9
	v_rcp_f32_e32 v9, v9
	v_cndmask_b32_e32 v2, v21, v2, vcc
	v_mul_f32_e32 v10, v9, v10
	v_cndmask_b32_e32 v9, v9, v10, vcc
	v_mul_f32_e32 v10, 0xbfb8aa3b, v11
	v_exp_f32_e32 v10, v10
	v_mul_f32_e32 v11, v11, v16
	v_add_f32_e32 v10, 1.0, v10
	v_rcp_f32_e32 v10, v10
	s_nop 0
	v_mul_f32_e32 v11, v10, v11
	v_cndmask_b32_e32 v10, v10, v11, vcc
	v_mul_f32_e32 v11, 0xbfb8aa3b, v4
	v_exp_f32_e32 v11, v11
	v_mul_f32_e32 v4, v4, v17
	v_add_f32_e32 v11, 1.0, v11
	v_rcp_f32_e32 v11, v11
	s_nop 0
	v_mul_f32_e32 v4, v11, v4
	v_cndmask_b32_e32 v11, v11, v4, vcc
	v_mul_f32_e32 v4, 0xbfb8aa3b, v5
	v_exp_f32_e32 v4, v4
	v_mul_f32_e32 v5, v5, v18
	v_add_f32_e32 v4, 1.0, v4
	v_rcp_f32_e32 v4, v4
	s_nop 0
	v_mul_f32_e32 v5, v4, v5
	v_cndmask_b32_e32 v14, v4, v5, vcc
	v_mul_f32_e32 v4, 0xbfb8aa3b, v6
	v_exp_f32_e32 v4, v4
	v_mul_f32_e32 v5, v6, v19
	v_cvt_pk_bf16_f32 v6, v11, v14
	v_add_f32_e32 v4, 1.0, v4
	v_rcp_f32_e32 v4, v4
	s_nop 0
	v_mul_f32_e32 v5, v4, v5
	v_cndmask_b32_e32 v15, v4, v5, vcc
	v_mul_f32_e32 v4, 0xbfb8aa3b, v7
	v_exp_f32_e32 v4, v4
	v_mul_f32_e32 v5, v7, v20
	v_add_f32_e32 v4, 1.0, v4
	v_rcp_f32_e32 v4, v4
	s_nop 0
	v_mul_f32_e32 v5, v4, v5
	v_cndmask_b32_e32 v7, v4, v5, vcc
	v_cvt_pk_bf16_f32 v4, v2, v8
	v_cvt_pk_bf16_f32 v5, v9, v10
	v_cvt_pk_bf16_f32 v7, v15, v7
	global_store_dwordx4 v[12:13], v[4:7], off offset:256
	s_andn2_b64 vcc, exec, s[40:41]
	s_mov_b64 s[6:7], -1
	s_cbranch_vccnz .LBB0_690
	s_andn2_b64 vcc, exec, s[34:35]
	s_cbranch_vccnz .LBB0_689
	s_barrier
	s_branch .LBB0_689
